# prompt scan loaders: fragments staged HBM -> registers (8 chunks ahead) -> 6-slot LDS ring instead of LDS-DMA 5 ahead (13 chunks of lookahead against memory latency under load)
# baseline (speedup 1.0000x reference)
; #define LDSBAR() do { asm volatile("s_waitcnt lgkmcnt(0)" ::: "memory"); __builtin_amdgcn_s_barrier(); asm volatile("" ::: "memory"); } while (0)
; #define HG_STORE(R, s) do { LAS unsigned char* d_ = ring + (s) * HG_SLOT; *(LAS v4u*)(d_ + 16 * tid) = R.q; if (vload) *(LAS v4u*)(d_ + 16384 + 16 * tid) = R.v; *(LAS v4u*)(d_ + 8192 + 16 * tid) = R.l0; \
;         if (tid < 160) *(LAS v4u*)(d_ + 24576 + 16 * tid) = R.l1; } while (0)
; __device__ __forceinline__ void hg_seq(const Frame& F, unsigned char* ws, const float* s0, float* sout, float* Og, int seq, bool sample, int vs_base, int nvs) {
;     ...
;     HgPre R0, R1, R2, R3, R4, R5;
;     R0.l1 = R0.v = (v4u){0u, 0u, 0u, 0u}; R1.l1 = R1.v = (v4u){0u, 0u, 0u, 0u}; R2.l1 = R2.v = (v4u){0u, 0u, 0u, 0u}; R3.l1 = R3.v = (v4u){0u, 0u, 0u, 0u}; R4.l1 = R4.v = (v4u){0u, 0u, 0u, 0u}; R5.l1 = R5.v = (v4u){0u, 0u, 0u, 0u};
;     HG_LOAD(R0, 0); HG_LOAD(R1, 1); HG_LOAD(R2, 2); HG_LOAD(R3, 3); HG_LOAD(R4, 4);
;     HG_STORE(R0, 0); LDSBAR();
;     for (int n = 0; n < nch; n += 6) {
;         HG_LOAD(R5, n + 5); if (active) hg_chunk(ring, S, Ob + (size_t)(n + 0) * 32 * DA, nvalid, vs, lane); if (n + 1 < nch) HG_STORE(R1, 1); LDSBAR(); if (n + 1 >= nch) break;
;         HG_LOAD(R0, n + 6); if (active) hg_chunk(ring + HG_SLOT, S, Ob + (size_t)(n + 1) * 32 * DA, nvalid, vs, lane); if (n + 2 < nch) HG_STORE(R2, 0); LDSBAR(); if (n + 2 >= nch) break;
;         HG_LOAD(R1, n + 7); if (active) hg_chunk(ring, S, Ob + (size_t)(n + 2) * 32 * DA, nvalid, vs, lane); if (n + 3 < nch) HG_STORE(R3, 1); LDSBAR(); if (n + 3 >= nch) break;
;         HG_LOAD(R2, n + 8); if (active) hg_chunk(ring + HG_SLOT, S, Ob + (size_t)(n + 3) * 32 * DA, nvalid, vs, lane); if (n + 4 < nch) HG_STORE(R4, 0); LDSBAR(); if (n + 4 >= nch) break;
;         HG_LOAD(R3, n + 9); if (active) hg_chunk(ring, S, Ob + (size_t)(n + 4) * 32 * DA, nvalid, vs, lane); if (n + 5 < nch) HG_STORE(R5, 1); LDSBAR(); if (n + 5 >= nch) break;
;         HG_LOAD(R4, n + 10); if (active) hg_chunk(ring + HG_SLOT, S, Ob + (size_t)(n + 5) * 32 * DA, nvalid, vs, lane); if (n + 6 < nch) HG_STORE(R0, 0); LDSBAR();
.Lscan_ld_w7_skip:
.Lscan_ld_go:
	v_lshlrev_b32_e32 v1, 4, v189
	v_add_u32_e32 v2, s46, v1
	v_mov_b32_e32 v144, v2
	v_add_u32_e32 v2, s47, v1
	v_mov_b32_e32 v145, v2
	v_add_u32_e32 v2, s48, v1
	v_mov_b32_e32 v146, v2
	v_add_u32_e32 v2, s49, v1
	v_mov_b32_e32 v147, v2
	v_add_u32_e32 v2, s46, v1
	v_add_u32_e32 v148, 0x5400, v2
	v_add_u32_e32 v2, s47, v1
	v_add_u32_e32 v149, 0x5400, v2
	v_add_u32_e32 v2, s48, v1
	v_add_u32_e32 v150, 0x5400, v2
	v_add_u32_e32 v2, s49, v1
	v_add_u32_e32 v151, 0x5400, v2
	v_add_u32_e32 v2, s46, v1
	v_add_u32_e32 v152, 0xa800, v2
	v_add_u32_e32 v2, s47, v1
	v_add_u32_e32 v153, 0xa800, v2
	v_add_u32_e32 v2, s48, v1
	v_add_u32_e32 v154, 0xa800, v2
	v_add_u32_e32 v2, s49, v1
	v_add_u32_e32 v155, 0xa800, v2
	v_add_u32_e32 v2, s46, v1
	v_add_u32_e32 v156, 0xfc00, v2
	v_add_u32_e32 v2, s47, v1
	v_add_u32_e32 v157, 0xfc00, v2
	v_add_u32_e32 v2, s48, v1
	v_add_u32_e32 v158, 0xfc00, v2
	v_add_u32_e32 v2, s49, v1
	v_add_u32_e32 v159, 0xfc00, v2
	v_add_u32_e32 v2, s46, v1
	v_add_u32_e32 v160, 0x15000, v2
	v_add_u32_e32 v2, s47, v1
	v_add_u32_e32 v161, 0x15000, v2
	v_add_u32_e32 v2, s48, v1
	v_add_u32_e32 v163, 0x15000, v2
	v_add_u32_e32 v2, s49, v1
	v_add_u32_e32 v164, 0x15000, v2
	v_add_u32_e32 v2, s46, v1
	v_add_u32_e32 v165, 0x1a400, v2
	v_add_u32_e32 v2, s47, v1
	v_add_u32_e32 v166, 0x1a400, v2
	v_add_u32_e32 v2, s48, v1
	v_add_u32_e32 v167, 0x1a400, v2
	v_add_u32_e32 v2, s49, v1
	v_add_u32_e32 v168, 0x1a400, v2
	global_load_dwordx4 v[16:19], v[8:9], off
	global_load_dwordx4 v[20:23], v[10:11], off
	global_load_dwordx4 v[24:27], v[12:13], off
	global_load_dwordx4 v[28:31], v[14:15], off
	v_lshl_add_u64 v[8:9], v[8:9], 0, s[52:53]
	v_lshl_add_u64 v[10:11], v[10:11], 0, s[54:55]
	v_lshl_add_u64 v[12:13], v[12:13], 0, s[56:57]
	v_lshl_add_u64 v[14:15], v[14:15], 0, s[58:59]
	global_load_dwordx4 v[32:35], v[8:9], off
	global_load_dwordx4 v[36:39], v[10:11], off
	global_load_dwordx4 v[40:43], v[12:13], off
	global_load_dwordx4 v[44:47], v[14:15], off
	v_lshl_add_u64 v[8:9], v[8:9], 0, s[52:53]
	v_lshl_add_u64 v[10:11], v[10:11], 0, s[54:55]
	v_lshl_add_u64 v[12:13], v[12:13], 0, s[56:57]
	v_lshl_add_u64 v[14:15], v[14:15], 0, s[58:59]
	global_load_dwordx4 v[48:51], v[8:9], off
	global_load_dwordx4 v[52:55], v[10:11], off
	global_load_dwordx4 v[56:59], v[12:13], off
	global_load_dwordx4 v[60:63], v[14:15], off
	v_lshl_add_u64 v[8:9], v[8:9], 0, s[52:53]
	v_lshl_add_u64 v[10:11], v[10:11], 0, s[54:55]
	v_lshl_add_u64 v[12:13], v[12:13], 0, s[56:57]
	v_lshl_add_u64 v[14:15], v[14:15], 0, s[58:59]
	global_load_dwordx4 v[64:67], v[8:9], off
	global_load_dwordx4 v[68:71], v[10:11], off
	global_load_dwordx4 v[72:75], v[12:13], off
	global_load_dwordx4 v[76:79], v[14:15], off
	v_lshl_add_u64 v[8:9], v[8:9], 0, s[52:53]
	v_lshl_add_u64 v[10:11], v[10:11], 0, s[54:55]
	v_lshl_add_u64 v[12:13], v[12:13], 0, s[56:57]
	v_lshl_add_u64 v[14:15], v[14:15], 0, s[58:59]
	global_load_dwordx4 v[80:83], v[8:9], off
	global_load_dwordx4 v[84:87], v[10:11], off
	global_load_dwordx4 v[88:91], v[12:13], off
	global_load_dwordx4 v[92:95], v[14:15], off
	v_lshl_add_u64 v[8:9], v[8:9], 0, s[52:53]
	v_lshl_add_u64 v[10:11], v[10:11], 0, s[54:55]
	v_lshl_add_u64 v[12:13], v[12:13], 0, s[56:57]
	v_lshl_add_u64 v[14:15], v[14:15], 0, s[58:59]
	global_load_dwordx4 v[96:99], v[8:9], off
	global_load_dwordx4 v[100:103], v[10:11], off
	global_load_dwordx4 v[104:107], v[12:13], off
	global_load_dwordx4 v[108:111], v[14:15], off
	v_lshl_add_u64 v[8:9], v[8:9], 0, s[52:53]
	v_lshl_add_u64 v[10:11], v[10:11], 0, s[54:55]
	v_lshl_add_u64 v[12:13], v[12:13], 0, s[56:57]
	v_lshl_add_u64 v[14:15], v[14:15], 0, s[58:59]
	global_load_dwordx4 v[112:115], v[8:9], off
	global_load_dwordx4 v[116:119], v[10:11], off
	global_load_dwordx4 v[120:123], v[12:13], off
	global_load_dwordx4 v[124:127], v[14:15], off
	v_lshl_add_u64 v[8:9], v[8:9], 0, s[52:53]
	v_lshl_add_u64 v[10:11], v[10:11], 0, s[54:55]
	v_lshl_add_u64 v[12:13], v[12:13], 0, s[56:57]
	v_lshl_add_u64 v[14:15], v[14:15], 0, s[58:59]
	global_load_dwordx4 v[128:131], v[8:9], off
	global_load_dwordx4 v[132:135], v[10:11], off
	global_load_dwordx4 v[136:139], v[12:13], off
	global_load_dwordx4 v[140:143], v[14:15], off
	v_lshl_add_u64 v[8:9], v[8:9], 0, s[52:53]
	v_lshl_add_u64 v[10:11], v[10:11], 0, s[54:55]
	v_lshl_add_u64 v[12:13], v[12:13], 0, s[56:57]
	v_lshl_add_u64 v[14:15], v[14:15], 0, s[58:59]
	s_waitcnt vmcnt(28)
	ds_write_b128 v144, v[16:19]
	ds_write_b128 v145, v[20:23]
	ds_write_b128 v146, v[24:27]
	ds_write_b128 v147, v[28:31]
	global_load_dwordx4 v[16:19], v[8:9], off
	global_load_dwordx4 v[20:23], v[10:11], off
	global_load_dwordx4 v[24:27], v[12:13], off
	global_load_dwordx4 v[28:31], v[14:15], off
	v_lshl_add_u64 v[8:9], v[8:9], 0, s[52:53]
	v_lshl_add_u64 v[10:11], v[10:11], 0, s[54:55]
	v_lshl_add_u64 v[12:13], v[12:13], 0, s[56:57]
	v_lshl_add_u64 v[14:15], v[14:15], 0, s[58:59]
	s_waitcnt vmcnt(28)
	ds_write_b128 v148, v[32:35]
	ds_write_b128 v149, v[36:39]
	ds_write_b128 v150, v[40:43]
	ds_write_b128 v151, v[44:47]
	global_load_dwordx4 v[32:35], v[8:9], off
	global_load_dwordx4 v[36:39], v[10:11], off
	global_load_dwordx4 v[40:43], v[12:13], off
	global_load_dwordx4 v[44:47], v[14:15], off
	v_lshl_add_u64 v[8:9], v[8:9], 0, s[52:53]
	v_lshl_add_u64 v[10:11], v[10:11], 0, s[54:55]
	v_lshl_add_u64 v[12:13], v[12:13], 0, s[56:57]
	v_lshl_add_u64 v[14:15], v[14:15], 0, s[58:59]
	s_waitcnt vmcnt(28)
	ds_write_b128 v152, v[48:51]
	ds_write_b128 v153, v[52:55]
	ds_write_b128 v154, v[56:59]
	ds_write_b128 v155, v[60:63]
	global_load_dwordx4 v[48:51], v[8:9], off
	global_load_dwordx4 v[52:55], v[10:11], off
	global_load_dwordx4 v[56:59], v[12:13], off
	global_load_dwordx4 v[60:63], v[14:15], off
	v_lshl_add_u64 v[8:9], v[8:9], 0, s[52:53]
	v_lshl_add_u64 v[10:11], v[10:11], 0, s[54:55]
	v_lshl_add_u64 v[12:13], v[12:13], 0, s[56:57]
	v_lshl_add_u64 v[14:15], v[14:15], 0, s[58:59]
	s_waitcnt vmcnt(28)
	ds_write_b128 v156, v[64:67]
	ds_write_b128 v157, v[68:71]
	ds_write_b128 v158, v[72:75]
	ds_write_b128 v159, v[76:79]
	global_load_dwordx4 v[64:67], v[8:9], off
	global_load_dwordx4 v[68:71], v[10:11], off
	global_load_dwordx4 v[72:75], v[12:13], off
	global_load_dwordx4 v[76:79], v[14:15], off
	v_lshl_add_u64 v[8:9], v[8:9], 0, s[52:53]
	v_lshl_add_u64 v[10:11], v[10:11], 0, s[54:55]
	v_lshl_add_u64 v[12:13], v[12:13], 0, s[56:57]
	v_lshl_add_u64 v[14:15], v[14:15], 0, s[58:59]
	s_waitcnt vmcnt(28)
	ds_write_b128 v160, v[80:83]
	ds_write_b128 v161, v[84:87]
	ds_write_b128 v163, v[88:91]
	ds_write_b128 v164, v[92:95]
	global_load_dwordx4 v[80:83], v[8:9], off
	global_load_dwordx4 v[84:87], v[10:11], off
	global_load_dwordx4 v[88:91], v[12:13], off
	global_load_dwordx4 v[92:95], v[14:15], off
	v_lshl_add_u64 v[8:9], v[8:9], 0, s[52:53]
	v_lshl_add_u64 v[10:11], v[10:11], 0, s[54:55]
	v_lshl_add_u64 v[12:13], v[12:13], 0, s[56:57]
	v_lshl_add_u64 v[14:15], v[14:15], 0, s[58:59]
	s_waitcnt lgkmcnt(0)
	s_barrier
; #define LDSBAR() do { asm volatile("s_waitcnt lgkmcnt(0)" ::: "memory"); __builtin_amdgcn_s_barrier(); asm volatile("" ::: "memory"); } while (0)
; #define HG_STORE(R, s) do { LAS unsigned char* d_ = ring + (s) * HG_SLOT; *(LAS v4u*)(d_ + 16 * tid) = R.q; if (vload) *(LAS v4u*)(d_ + 16384 + 16 * tid) = R.v; *(LAS v4u*)(d_ + 8192 + 16 * tid) = R.l0; \
;         if (tid < 160) *(LAS v4u*)(d_ + 24576 + 16 * tid) = R.l1; } while (0)
; __device__ __forceinline__ void hg_seq(const Frame& F, unsigned char* ws, const float* s0, float* sout, float* Og, int seq, bool sample, int vs_base, int nvs) {
;     ...
;     HgPre R0, R1, R2, R3, R4, R5;
;     R0.l1 = R0.v = (v4u){0u, 0u, 0u, 0u}; R1.l1 = R1.v = (v4u){0u, 0u, 0u, 0u}; R2.l1 = R2.v = (v4u){0u, 0u, 0u, 0u}; R3.l1 = R3.v = (v4u){0u, 0u, 0u, 0u}; R4.l1 = R4.v = (v4u){0u, 0u, 0u, 0u}; R5.l1 = R5.v = (v4u){0u, 0u, 0u, 0u};
;     HG_LOAD(R0, 0); HG_LOAD(R1, 1); HG_LOAD(R2, 2); HG_LOAD(R3, 3); HG_LOAD(R4, 4);
;     HG_STORE(R0, 0); LDSBAR();
;     for (int n = 0; n < nch; n += 6) {
;         HG_LOAD(R5, n + 5); if (active) hg_chunk(ring, S, Ob + (size_t)(n + 0) * 32 * DA, nvalid, vs, lane); if (n + 1 < nch) HG_STORE(R1, 1); LDSBAR(); if (n + 1 >= nch) break;
;         HG_LOAD(R0, n + 6); if (active) hg_chunk(ring + HG_SLOT, S, Ob + (size_t)(n + 1) * 32 * DA, nvalid, vs, lane); if (n + 2 < nch) HG_STORE(R2, 0); LDSBAR(); if (n + 2 >= nch) break;
;         HG_LOAD(R1, n + 7); if (active) hg_chunk(ring, S, Ob + (size_t)(n + 2) * 32 * DA, nvalid, vs, lane); if (n + 3 < nch) HG_STORE(R3, 1); LDSBAR(); if (n + 3 >= nch) break;
;         HG_LOAD(R2, n + 8); if (active) hg_chunk(ring + HG_SLOT, S, Ob + (size_t)(n + 3) * 32 * DA, nvalid, vs, lane); if (n + 4 < nch) HG_STORE(R4, 0); LDSBAR(); if (n + 4 >= nch) break;
;         HG_LOAD(R3, n + 9); if (active) hg_chunk(ring, S, Ob + (size_t)(n + 4) * 32 * DA, nvalid, vs, lane); if (n + 5 < nch) HG_STORE(R5, 1); LDSBAR(); if (n + 5 >= nch) break;
;         HG_LOAD(R4, n + 10); if (active) hg_chunk(ring + HG_SLOT, S, Ob + (size_t)(n + 5) * 32 * DA, nvalid, vs, lane); if (n + 6 < nch) HG_STORE(R0, 0); LDSBAR();
	s_waitcnt vmcnt(28)
	ds_write_b128 v165, v[96:99]
	ds_write_b128 v166, v[100:103]
	ds_write_b128 v167, v[104:107]
	ds_write_b128 v168, v[108:111]
	global_load_dwordx4 v[96:99], v[8:9], off
	global_load_dwordx4 v[100:103], v[10:11], off
	global_load_dwordx4 v[104:107], v[12:13], off
	global_load_dwordx4 v[108:111], v[14:15], off
	v_lshl_add_u64 v[8:9], v[8:9], 0, s[52:53]
	v_lshl_add_u64 v[10:11], v[10:11], 0, s[54:55]
	v_lshl_add_u64 v[12:13], v[12:13], 0, s[56:57]
	v_lshl_add_u64 v[14:15], v[14:15], 0, s[58:59]
	s_waitcnt lgkmcnt(0)
	s_barrier
	s_waitcnt vmcnt(28)
	ds_write_b128 v144, v[112:115]
	ds_write_b128 v145, v[116:119]
	ds_write_b128 v146, v[120:123]
	ds_write_b128 v147, v[124:127]
	global_load_dwordx4 v[112:115], v[8:9], off
	global_load_dwordx4 v[116:119], v[10:11], off
	global_load_dwordx4 v[120:123], v[12:13], off
	global_load_dwordx4 v[124:127], v[14:15], off
	v_lshl_add_u64 v[8:9], v[8:9], 0, s[52:53]
	v_lshl_add_u64 v[10:11], v[10:11], 0, s[54:55]
	v_lshl_add_u64 v[12:13], v[12:13], 0, s[56:57]
	v_lshl_add_u64 v[14:15], v[14:15], 0, s[58:59]
	s_waitcnt lgkmcnt(0)
	s_barrier
	s_waitcnt vmcnt(28)
	ds_write_b128 v148, v[128:131]
	ds_write_b128 v149, v[132:135]
	ds_write_b128 v150, v[136:139]
	ds_write_b128 v151, v[140:143]
	global_load_dwordx4 v[128:131], v[8:9], off
	global_load_dwordx4 v[132:135], v[10:11], off
	global_load_dwordx4 v[136:139], v[12:13], off
	global_load_dwordx4 v[140:143], v[14:15], off
	v_lshl_add_u64 v[8:9], v[8:9], 0, s[52:53]
	v_lshl_add_u64 v[10:11], v[10:11], 0, s[54:55]
	v_lshl_add_u64 v[12:13], v[12:13], 0, s[56:57]
	v_lshl_add_u64 v[14:15], v[14:15], 0, s[58:59]
	s_waitcnt lgkmcnt(0)
	s_barrier
	s_waitcnt vmcnt(28)
	ds_write_b128 v152, v[16:19]
	ds_write_b128 v153, v[20:23]
	ds_write_b128 v154, v[24:27]
	ds_write_b128 v155, v[28:31]
	global_load_dwordx4 v[16:19], v[8:9], off
	global_load_dwordx4 v[20:23], v[10:11], off
	global_load_dwordx4 v[24:27], v[12:13], off
	global_load_dwordx4 v[28:31], v[14:15], off
	v_lshl_add_u64 v[8:9], v[8:9], 0, s[52:53]
	v_lshl_add_u64 v[10:11], v[10:11], 0, s[54:55]
	v_lshl_add_u64 v[12:13], v[12:13], 0, s[56:57]
	v_lshl_add_u64 v[14:15], v[14:15], 0, s[58:59]
	s_waitcnt lgkmcnt(0)
	s_barrier
	s_waitcnt vmcnt(28)
	ds_write_b128 v156, v[32:35]
	ds_write_b128 v157, v[36:39]
	ds_write_b128 v158, v[40:43]
	ds_write_b128 v159, v[44:47]
	global_load_dwordx4 v[32:35], v[8:9], off
	global_load_dwordx4 v[36:39], v[10:11], off
	global_load_dwordx4 v[40:43], v[12:13], off
	global_load_dwordx4 v[44:47], v[14:15], off
	v_lshl_add_u64 v[8:9], v[8:9], 0, s[52:53]
	v_lshl_add_u64 v[10:11], v[10:11], 0, s[54:55]
	v_lshl_add_u64 v[12:13], v[12:13], 0, s[56:57]
	v_lshl_add_u64 v[14:15], v[14:15], 0, s[58:59]
	s_waitcnt lgkmcnt(0)
	s_barrier
	s_waitcnt vmcnt(28)
	ds_write_b128 v160, v[48:51]
	ds_write_b128 v161, v[52:55]
	ds_write_b128 v163, v[56:59]
	ds_write_b128 v164, v[60:63]
	global_load_dwordx4 v[48:51], v[8:9], off
	global_load_dwordx4 v[52:55], v[10:11], off
	global_load_dwordx4 v[56:59], v[12:13], off
	global_load_dwordx4 v[60:63], v[14:15], off
	v_lshl_add_u64 v[8:9], v[8:9], 0, s[52:53]
	v_lshl_add_u64 v[10:11], v[10:11], 0, s[54:55]
	v_lshl_add_u64 v[12:13], v[12:13], 0, s[56:57]
	v_lshl_add_u64 v[14:15], v[14:15], 0, s[58:59]
	s_waitcnt lgkmcnt(0)
	s_barrier
	s_waitcnt vmcnt(28)
	ds_write_b128 v165, v[64:67]
	ds_write_b128 v166, v[68:71]
	ds_write_b128 v167, v[72:75]
	ds_write_b128 v168, v[76:79]
	global_load_dwordx4 v[64:67], v[8:9], off
	global_load_dwordx4 v[68:71], v[10:11], off
	global_load_dwordx4 v[72:75], v[12:13], off
	global_load_dwordx4 v[76:79], v[14:15], off
	v_lshl_add_u64 v[8:9], v[8:9], 0, s[52:53]
	v_lshl_add_u64 v[10:11], v[10:11], 0, s[54:55]
	v_lshl_add_u64 v[12:13], v[12:13], 0, s[56:57]
	v_lshl_add_u64 v[14:15], v[14:15], 0, s[58:59]
	s_waitcnt lgkmcnt(0)
	s_barrier
	s_waitcnt vmcnt(28)
	ds_write_b128 v144, v[80:83]
	ds_write_b128 v145, v[84:87]
	ds_write_b128 v146, v[88:91]
	ds_write_b128 v147, v[92:95]
	global_load_dwordx4 v[80:83], v[8:9], off
	global_load_dwordx4 v[84:87], v[10:11], off
	global_load_dwordx4 v[88:91], v[12:13], off
	global_load_dwordx4 v[92:95], v[14:15], off
	v_lshl_add_u64 v[8:9], v[8:9], 0, s[52:53]
	v_lshl_add_u64 v[10:11], v[10:11], 0, s[54:55]
	v_lshl_add_u64 v[12:13], v[12:13], 0, s[56:57]
	v_lshl_add_u64 v[14:15], v[14:15], 0, s[58:59]
	s_waitcnt lgkmcnt(0)
	s_barrier
	s_waitcnt vmcnt(28)
	ds_write_b128 v148, v[96:99]
	ds_write_b128 v149, v[100:103]
	ds_write_b128 v150, v[104:107]
	ds_write_b128 v151, v[108:111]
	global_load_dwordx4 v[96:99], v[8:9], off
	global_load_dwordx4 v[100:103], v[10:11], off
	global_load_dwordx4 v[104:107], v[12:13], off
	global_load_dwordx4 v[108:111], v[14:15], off
	v_lshl_add_u64 v[8:9], v[8:9], 0, s[52:53]
	v_lshl_add_u64 v[10:11], v[10:11], 0, s[54:55]
	v_lshl_add_u64 v[12:13], v[12:13], 0, s[56:57]
	v_lshl_add_u64 v[14:15], v[14:15], 0, s[58:59]
	s_waitcnt lgkmcnt(0)
	s_barrier
	s_waitcnt vmcnt(28)
	ds_write_b128 v152, v[112:115]
	ds_write_b128 v153, v[116:119]
	ds_write_b128 v154, v[120:123]
	ds_write_b128 v155, v[124:127]
	global_load_dwordx4 v[112:115], v[8:9], off
	global_load_dwordx4 v[116:119], v[10:11], off
	global_load_dwordx4 v[120:123], v[12:13], off
	global_load_dwordx4 v[124:127], v[14:15], off
	v_lshl_add_u64 v[8:9], v[8:9], 0, s[52:53]
	v_lshl_add_u64 v[10:11], v[10:11], 0, s[54:55]
	v_lshl_add_u64 v[12:13], v[12:13], 0, s[56:57]
	v_lshl_add_u64 v[14:15], v[14:15], 0, s[58:59]
	s_waitcnt lgkmcnt(0)
	s_barrier
; #define LDSBAR() do { asm volatile("s_waitcnt lgkmcnt(0)" ::: "memory"); __builtin_amdgcn_s_barrier(); asm volatile("" ::: "memory"); } while (0)
; #define HG_STORE(R, s) do { LAS unsigned char* d_ = ring + (s) * HG_SLOT; *(LAS v4u*)(d_ + 16 * tid) = R.q; if (vload) *(LAS v4u*)(d_ + 16384 + 16 * tid) = R.v; *(LAS v4u*)(d_ + 8192 + 16 * tid) = R.l0; \
;         if (tid < 160) *(LAS v4u*)(d_ + 24576 + 16 * tid) = R.l1; } while (0)
; __device__ __forceinline__ void hg_seq(const Frame& F, unsigned char* ws, const float* s0, float* sout, float* Og, int seq, bool sample, int vs_base, int nvs) {
;     ...
;     HgPre R0, R1, R2, R3, R4, R5;
;     R0.l1 = R0.v = (v4u){0u, 0u, 0u, 0u}; R1.l1 = R1.v = (v4u){0u, 0u, 0u, 0u}; R2.l1 = R2.v = (v4u){0u, 0u, 0u, 0u}; R3.l1 = R3.v = (v4u){0u, 0u, 0u, 0u}; R4.l1 = R4.v = (v4u){0u, 0u, 0u, 0u}; R5.l1 = R5.v = (v4u){0u, 0u, 0u, 0u};
;     HG_LOAD(R0, 0); HG_LOAD(R1, 1); HG_LOAD(R2, 2); HG_LOAD(R3, 3); HG_LOAD(R4, 4);
;     HG_STORE(R0, 0); LDSBAR();
;     for (int n = 0; n < nch; n += 6) {
;         HG_LOAD(R5, n + 5); if (active) hg_chunk(ring, S, Ob + (size_t)(n + 0) * 32 * DA, nvalid, vs, lane); if (n + 1 < nch) HG_STORE(R1, 1); LDSBAR(); if (n + 1 >= nch) break;
;         HG_LOAD(R0, n + 6); if (active) hg_chunk(ring + HG_SLOT, S, Ob + (size_t)(n + 1) * 32 * DA, nvalid, vs, lane); if (n + 2 < nch) HG_STORE(R2, 0); LDSBAR(); if (n + 2 >= nch) break;
;         HG_LOAD(R1, n + 7); if (active) hg_chunk(ring, S, Ob + (size_t)(n + 2) * 32 * DA, nvalid, vs, lane); if (n + 3 < nch) HG_STORE(R3, 1); LDSBAR(); if (n + 3 >= nch) break;
;         HG_LOAD(R2, n + 8); if (active) hg_chunk(ring + HG_SLOT, S, Ob + (size_t)(n + 3) * 32 * DA, nvalid, vs, lane); if (n + 4 < nch) HG_STORE(R4, 0); LDSBAR(); if (n + 4 >= nch) break;
;         HG_LOAD(R3, n + 9); if (active) hg_chunk(ring, S, Ob + (size_t)(n + 4) * 32 * DA, nvalid, vs, lane); if (n + 5 < nch) HG_STORE(R5, 1); LDSBAR(); if (n + 5 >= nch) break;
;         HG_LOAD(R4, n + 10); if (active) hg_chunk(ring + HG_SLOT, S, Ob + (size_t)(n + 5) * 32 * DA, nvalid, vs, lane); if (n + 6 < nch) HG_STORE(R0, 0); LDSBAR();
	s_waitcnt vmcnt(28)
	ds_write_b128 v156, v[128:131]
	ds_write_b128 v157, v[132:135]
	ds_write_b128 v158, v[136:139]
	ds_write_b128 v159, v[140:143]
	global_load_dwordx4 v[128:131], v[8:9], off
	global_load_dwordx4 v[132:135], v[10:11], off
	global_load_dwordx4 v[136:139], v[12:13], off
	global_load_dwordx4 v[140:143], v[14:15], off
	v_lshl_add_u64 v[8:9], v[8:9], 0, s[52:53]
	v_lshl_add_u64 v[10:11], v[10:11], 0, s[54:55]
	v_lshl_add_u64 v[12:13], v[12:13], 0, s[56:57]
	v_lshl_add_u64 v[14:15], v[14:15], 0, s[58:59]
	s_waitcnt lgkmcnt(0)
	s_barrier
	s_waitcnt vmcnt(28)
	ds_write_b128 v160, v[16:19]
	ds_write_b128 v161, v[20:23]
	ds_write_b128 v163, v[24:27]
	ds_write_b128 v164, v[28:31]
	global_load_dwordx4 v[16:19], v[8:9], off
	global_load_dwordx4 v[20:23], v[10:11], off
	global_load_dwordx4 v[24:27], v[12:13], off
	global_load_dwordx4 v[28:31], v[14:15], off
	v_lshl_add_u64 v[8:9], v[8:9], 0, s[52:53]
	v_lshl_add_u64 v[10:11], v[10:11], 0, s[54:55]
	v_lshl_add_u64 v[12:13], v[12:13], 0, s[56:57]
	v_lshl_add_u64 v[14:15], v[14:15], 0, s[58:59]
	s_waitcnt lgkmcnt(0)
	s_barrier
	s_waitcnt vmcnt(28)
	ds_write_b128 v165, v[32:35]
	ds_write_b128 v166, v[36:39]
	ds_write_b128 v167, v[40:43]
	ds_write_b128 v168, v[44:47]
	global_load_dwordx4 v[32:35], v[8:9], off
	global_load_dwordx4 v[36:39], v[10:11], off
	global_load_dwordx4 v[40:43], v[12:13], off
	global_load_dwordx4 v[44:47], v[14:15], off
	v_lshl_add_u64 v[8:9], v[8:9], 0, s[52:53]
	v_lshl_add_u64 v[10:11], v[10:11], 0, s[54:55]
	v_lshl_add_u64 v[12:13], v[12:13], 0, s[56:57]
	v_lshl_add_u64 v[14:15], v[14:15], 0, s[58:59]
	s_waitcnt lgkmcnt(0)
	s_barrier
	s_waitcnt vmcnt(28)
	ds_write_b128 v144, v[48:51]
	ds_write_b128 v145, v[52:55]
	ds_write_b128 v146, v[56:59]
	ds_write_b128 v147, v[60:63]
	global_load_dwordx4 v[48:51], v[8:9], off
	global_load_dwordx4 v[52:55], v[10:11], off
	global_load_dwordx4 v[56:59], v[12:13], off
	global_load_dwordx4 v[60:63], v[14:15], off
	v_lshl_add_u64 v[8:9], v[8:9], 0, s[52:53]
	v_lshl_add_u64 v[10:11], v[10:11], 0, s[54:55]
	v_lshl_add_u64 v[12:13], v[12:13], 0, s[56:57]
	v_lshl_add_u64 v[14:15], v[14:15], 0, s[58:59]
	s_waitcnt lgkmcnt(0)
	s_barrier
	s_waitcnt vmcnt(28)
	ds_write_b128 v148, v[64:67]
	ds_write_b128 v149, v[68:71]
	ds_write_b128 v150, v[72:75]
	ds_write_b128 v151, v[76:79]
	global_load_dwordx4 v[64:67], v[8:9], off
	global_load_dwordx4 v[68:71], v[10:11], off
	global_load_dwordx4 v[72:75], v[12:13], off
	global_load_dwordx4 v[76:79], v[14:15], off
	v_lshl_add_u64 v[8:9], v[8:9], 0, s[52:53]
	v_lshl_add_u64 v[10:11], v[10:11], 0, s[54:55]
	v_lshl_add_u64 v[12:13], v[12:13], 0, s[56:57]
	v_lshl_add_u64 v[14:15], v[14:15], 0, s[58:59]
	s_waitcnt lgkmcnt(0)
	s_barrier
	s_waitcnt vmcnt(28)
	ds_write_b128 v152, v[80:83]
	ds_write_b128 v153, v[84:87]
	ds_write_b128 v154, v[88:91]
	ds_write_b128 v155, v[92:95]
	global_load_dwordx4 v[80:83], v[8:9], off
	global_load_dwordx4 v[84:87], v[10:11], off
	global_load_dwordx4 v[88:91], v[12:13], off
	global_load_dwordx4 v[92:95], v[14:15], off
	v_lshl_add_u64 v[8:9], v[8:9], 0, s[52:53]
	v_lshl_add_u64 v[10:11], v[10:11], 0, s[54:55]
	v_lshl_add_u64 v[12:13], v[12:13], 0, s[56:57]
	v_lshl_add_u64 v[14:15], v[14:15], 0, s[58:59]
	s_waitcnt lgkmcnt(0)
	s_barrier
	s_waitcnt vmcnt(28)
	ds_write_b128 v156, v[96:99]
	ds_write_b128 v157, v[100:103]
	ds_write_b128 v158, v[104:107]
	ds_write_b128 v159, v[108:111]
	global_load_dwordx4 v[96:99], v[8:9], off
	global_load_dwordx4 v[100:103], v[10:11], off
	global_load_dwordx4 v[104:107], v[12:13], off
	global_load_dwordx4 v[108:111], v[14:15], off
	v_lshl_add_u64 v[8:9], v[8:9], 0, s[52:53]
	v_lshl_add_u64 v[10:11], v[10:11], 0, s[54:55]
	v_lshl_add_u64 v[12:13], v[12:13], 0, s[56:57]
	v_lshl_add_u64 v[14:15], v[14:15], 0, s[58:59]
	s_waitcnt lgkmcnt(0)
	s_barrier
	s_waitcnt vmcnt(28)
	ds_write_b128 v160, v[112:115]
	ds_write_b128 v161, v[116:119]
	ds_write_b128 v163, v[120:123]
	ds_write_b128 v164, v[124:127]
	global_load_dwordx4 v[112:115], v[8:9], off
	global_load_dwordx4 v[116:119], v[10:11], off
	global_load_dwordx4 v[120:123], v[12:13], off
	global_load_dwordx4 v[124:127], v[14:15], off
	v_lshl_add_u64 v[8:9], v[8:9], 0, s[52:53]
	v_lshl_add_u64 v[10:11], v[10:11], 0, s[54:55]
	v_lshl_add_u64 v[12:13], v[12:13], 0, s[56:57]
	v_lshl_add_u64 v[14:15], v[14:15], 0, s[58:59]
	s_waitcnt lgkmcnt(0)
	s_barrier
	s_waitcnt vmcnt(28)
	ds_write_b128 v165, v[128:131]
	ds_write_b128 v166, v[132:135]
	ds_write_b128 v167, v[136:139]
	ds_write_b128 v168, v[140:143]
	global_load_dwordx4 v[128:131], v[8:9], off
	global_load_dwordx4 v[132:135], v[10:11], off
	global_load_dwordx4 v[136:139], v[12:13], off
	global_load_dwordx4 v[140:143], v[14:15], off
	v_lshl_add_u64 v[8:9], v[8:9], 0, s[52:53]
	v_lshl_add_u64 v[10:11], v[10:11], 0, s[54:55]
	v_lshl_add_u64 v[12:13], v[12:13], 0, s[56:57]
	v_lshl_add_u64 v[14:15], v[14:15], 0, s[58:59]
	s_waitcnt lgkmcnt(0)
	s_barrier
	s_waitcnt vmcnt(28)
	ds_write_b128 v144, v[16:19]
	ds_write_b128 v145, v[20:23]
	ds_write_b128 v146, v[24:27]
	ds_write_b128 v147, v[28:31]
	global_load_dwordx4 v[16:19], v[8:9], off
	global_load_dwordx4 v[20:23], v[10:11], off
	global_load_dwordx4 v[24:27], v[12:13], off
	global_load_dwordx4 v[28:31], v[14:15], off
	v_lshl_add_u64 v[8:9], v[8:9], 0, s[52:53]
	v_lshl_add_u64 v[10:11], v[10:11], 0, s[54:55]
	v_lshl_add_u64 v[12:13], v[12:13], 0, s[56:57]
	v_lshl_add_u64 v[14:15], v[14:15], 0, s[58:59]
	s_waitcnt lgkmcnt(0)
	s_barrier
; #define LDSBAR() do { asm volatile("s_waitcnt lgkmcnt(0)" ::: "memory"); __builtin_amdgcn_s_barrier(); asm volatile("" ::: "memory"); } while (0)
; #define HG_STORE(R, s) do { LAS unsigned char* d_ = ring + (s) * HG_SLOT; *(LAS v4u*)(d_ + 16 * tid) = R.q; if (vload) *(LAS v4u*)(d_ + 16384 + 16 * tid) = R.v; *(LAS v4u*)(d_ + 8192 + 16 * tid) = R.l0; \
;         if (tid < 160) *(LAS v4u*)(d_ + 24576 + 16 * tid) = R.l1; } while (0)
; __device__ __forceinline__ void hg_seq(const Frame& F, unsigned char* ws, const float* s0, float* sout, float* Og, int seq, bool sample, int vs_base, int nvs) {
;     ...
;     HgPre R0, R1, R2, R3, R4, R5;
;     R0.l1 = R0.v = (v4u){0u, 0u, 0u, 0u}; R1.l1 = R1.v = (v4u){0u, 0u, 0u, 0u}; R2.l1 = R2.v = (v4u){0u, 0u, 0u, 0u}; R3.l1 = R3.v = (v4u){0u, 0u, 0u, 0u}; R4.l1 = R4.v = (v4u){0u, 0u, 0u, 0u}; R5.l1 = R5.v = (v4u){0u, 0u, 0u, 0u};
;     HG_LOAD(R0, 0); HG_LOAD(R1, 1); HG_LOAD(R2, 2); HG_LOAD(R3, 3); HG_LOAD(R4, 4);
;     HG_STORE(R0, 0); LDSBAR();
;     for (int n = 0; n < nch; n += 6) {
;         HG_LOAD(R5, n + 5); if (active) hg_chunk(ring, S, Ob + (size_t)(n + 0) * 32 * DA, nvalid, vs, lane); if (n + 1 < nch) HG_STORE(R1, 1); LDSBAR(); if (n + 1 >= nch) break;
;         HG_LOAD(R0, n + 6); if (active) hg_chunk(ring + HG_SLOT, S, Ob + (size_t)(n + 1) * 32 * DA, nvalid, vs, lane); if (n + 2 < nch) HG_STORE(R2, 0); LDSBAR(); if (n + 2 >= nch) break;
;         HG_LOAD(R1, n + 7); if (active) hg_chunk(ring, S, Ob + (size_t)(n + 2) * 32 * DA, nvalid, vs, lane); if (n + 3 < nch) HG_STORE(R3, 1); LDSBAR(); if (n + 3 >= nch) break;
;         HG_LOAD(R2, n + 8); if (active) hg_chunk(ring + HG_SLOT, S, Ob + (size_t)(n + 3) * 32 * DA, nvalid, vs, lane); if (n + 4 < nch) HG_STORE(R4, 0); LDSBAR(); if (n + 4 >= nch) break;
;         HG_LOAD(R3, n + 9); if (active) hg_chunk(ring, S, Ob + (size_t)(n + 4) * 32 * DA, nvalid, vs, lane); if (n + 5 < nch) HG_STORE(R5, 1); LDSBAR(); if (n + 5 >= nch) break;
;         HG_LOAD(R4, n + 10); if (active) hg_chunk(ring + HG_SLOT, S, Ob + (size_t)(n + 5) * 32 * DA, nvalid, vs, lane); if (n + 6 < nch) HG_STORE(R0, 0); LDSBAR();
	s_waitcnt vmcnt(28)
	ds_write_b128 v148, v[32:35]
	ds_write_b128 v149, v[36:39]
	ds_write_b128 v150, v[40:43]
	ds_write_b128 v151, v[44:47]
	global_load_dwordx4 v[32:35], v[8:9], off
	global_load_dwordx4 v[36:39], v[10:11], off
	global_load_dwordx4 v[40:43], v[12:13], off
	global_load_dwordx4 v[44:47], v[14:15], off
	v_lshl_add_u64 v[8:9], v[8:9], 0, s[52:53]
	v_lshl_add_u64 v[10:11], v[10:11], 0, s[54:55]
	v_lshl_add_u64 v[12:13], v[12:13], 0, s[56:57]
	v_lshl_add_u64 v[14:15], v[14:15], 0, s[58:59]
	s_waitcnt lgkmcnt(0)
	s_barrier
	s_waitcnt vmcnt(28)
	ds_write_b128 v152, v[48:51]
	ds_write_b128 v153, v[52:55]
	ds_write_b128 v154, v[56:59]
	ds_write_b128 v155, v[60:63]
	global_load_dwordx4 v[48:51], v[8:9], off
	global_load_dwordx4 v[52:55], v[10:11], off
	global_load_dwordx4 v[56:59], v[12:13], off
	global_load_dwordx4 v[60:63], v[14:15], off
	v_lshl_add_u64 v[8:9], v[8:9], 0, s[52:53]
	v_lshl_add_u64 v[10:11], v[10:11], 0, s[54:55]
	v_lshl_add_u64 v[12:13], v[12:13], 0, s[56:57]
	v_lshl_add_u64 v[14:15], v[14:15], 0, s[58:59]
	s_waitcnt lgkmcnt(0)
	s_barrier
	s_waitcnt vmcnt(28)
	ds_write_b128 v156, v[64:67]
	ds_write_b128 v157, v[68:71]
	ds_write_b128 v158, v[72:75]
	ds_write_b128 v159, v[76:79]
	global_load_dwordx4 v[64:67], v[8:9], off
	global_load_dwordx4 v[68:71], v[10:11], off
	global_load_dwordx4 v[72:75], v[12:13], off
	global_load_dwordx4 v[76:79], v[14:15], off
	v_lshl_add_u64 v[8:9], v[8:9], 0, s[52:53]
	v_lshl_add_u64 v[10:11], v[10:11], 0, s[54:55]
	v_lshl_add_u64 v[12:13], v[12:13], 0, s[56:57]
	v_lshl_add_u64 v[14:15], v[14:15], 0, s[58:59]
	s_waitcnt lgkmcnt(0)
	s_barrier
	s_waitcnt vmcnt(28)
	ds_write_b128 v160, v[80:83]
	ds_write_b128 v161, v[84:87]
	ds_write_b128 v163, v[88:91]
	ds_write_b128 v164, v[92:95]
	global_load_dwordx4 v[80:83], v[8:9], off
	global_load_dwordx4 v[84:87], v[10:11], off
	global_load_dwordx4 v[88:91], v[12:13], off
	global_load_dwordx4 v[92:95], v[14:15], off
	v_lshl_add_u64 v[8:9], v[8:9], 0, s[52:53]
	v_lshl_add_u64 v[10:11], v[10:11], 0, s[54:55]
	v_lshl_add_u64 v[12:13], v[12:13], 0, s[56:57]
	v_lshl_add_u64 v[14:15], v[14:15], 0, s[58:59]
	s_waitcnt lgkmcnt(0)
	s_barrier
	s_waitcnt vmcnt(28)
	ds_write_b128 v165, v[96:99]
	ds_write_b128 v166, v[100:103]
	ds_write_b128 v167, v[104:107]
	ds_write_b128 v168, v[108:111]
	global_load_dwordx4 v[96:99], v[8:9], off
	global_load_dwordx4 v[100:103], v[10:11], off
	global_load_dwordx4 v[104:107], v[12:13], off
	global_load_dwordx4 v[108:111], v[14:15], off
	v_lshl_add_u64 v[8:9], v[8:9], 0, s[52:53]
	v_lshl_add_u64 v[10:11], v[10:11], 0, s[54:55]
	v_lshl_add_u64 v[12:13], v[12:13], 0, s[56:57]
	v_lshl_add_u64 v[14:15], v[14:15], 0, s[58:59]
	s_waitcnt lgkmcnt(0)
	s_barrier
	s_waitcnt vmcnt(28)
	ds_write_b128 v144, v[112:115]
	ds_write_b128 v145, v[116:119]
	ds_write_b128 v146, v[120:123]
	ds_write_b128 v147, v[124:127]
	global_load_dwordx4 v[112:115], v[8:9], off
	global_load_dwordx4 v[116:119], v[10:11], off
	global_load_dwordx4 v[120:123], v[12:13], off
	global_load_dwordx4 v[124:127], v[14:15], off
	v_lshl_add_u64 v[8:9], v[8:9], 0, s[52:53]
	v_lshl_add_u64 v[10:11], v[10:11], 0, s[54:55]
	v_lshl_add_u64 v[12:13], v[12:13], 0, s[56:57]
	v_lshl_add_u64 v[14:15], v[14:15], 0, s[58:59]
	s_waitcnt lgkmcnt(0)
	s_barrier
	s_waitcnt vmcnt(28)
	ds_write_b128 v148, v[128:131]
	ds_write_b128 v149, v[132:135]
	ds_write_b128 v150, v[136:139]
	ds_write_b128 v151, v[140:143]
	global_load_dwordx4 v[128:131], v[8:9], off
	global_load_dwordx4 v[132:135], v[10:11], off
	global_load_dwordx4 v[136:139], v[12:13], off
	global_load_dwordx4 v[140:143], v[14:15], off
	v_lshl_add_u64 v[8:9], v[8:9], 0, s[52:53]
	v_lshl_add_u64 v[10:11], v[10:11], 0, s[54:55]
	v_lshl_add_u64 v[12:13], v[12:13], 0, s[56:57]
	v_lshl_add_u64 v[14:15], v[14:15], 0, s[58:59]
	s_waitcnt lgkmcnt(0)
	s_barrier
	s_waitcnt vmcnt(28)
	ds_write_b128 v152, v[16:19]
	ds_write_b128 v153, v[20:23]
	ds_write_b128 v154, v[24:27]
	ds_write_b128 v155, v[28:31]
	global_load_dwordx4 v[16:19], v[8:9], off
	global_load_dwordx4 v[20:23], v[10:11], off
	global_load_dwordx4 v[24:27], v[12:13], off
	global_load_dwordx4 v[28:31], v[14:15], off
	v_lshl_add_u64 v[8:9], v[8:9], 0, s[52:53]
	v_lshl_add_u64 v[10:11], v[10:11], 0, s[54:55]
	v_lshl_add_u64 v[12:13], v[12:13], 0, s[56:57]
	v_lshl_add_u64 v[14:15], v[14:15], 0, s[58:59]
	s_waitcnt lgkmcnt(0)
	s_barrier
	s_waitcnt vmcnt(28)
	ds_write_b128 v156, v[32:35]
	ds_write_b128 v157, v[36:39]
	ds_write_b128 v158, v[40:43]
	ds_write_b128 v159, v[44:47]
	global_load_dwordx4 v[32:35], v[8:9], off
	global_load_dwordx4 v[36:39], v[10:11], off
	global_load_dwordx4 v[40:43], v[12:13], off
	global_load_dwordx4 v[44:47], v[14:15], off
	v_lshl_add_u64 v[8:9], v[8:9], 0, s[52:53]
	v_lshl_add_u64 v[10:11], v[10:11], 0, s[54:55]
	v_lshl_add_u64 v[12:13], v[12:13], 0, s[56:57]
	v_lshl_add_u64 v[14:15], v[14:15], 0, s[58:59]
	s_waitcnt lgkmcnt(0)
	s_barrier
	s_waitcnt vmcnt(28)
	ds_write_b128 v160, v[48:51]
	ds_write_b128 v161, v[52:55]
	ds_write_b128 v163, v[56:59]
	ds_write_b128 v164, v[60:63]
	global_load_dwordx4 v[48:51], v[8:9], off
	global_load_dwordx4 v[52:55], v[10:11], off
	global_load_dwordx4 v[56:59], v[12:13], off
	global_load_dwordx4 v[60:63], v[14:15], off
	v_lshl_add_u64 v[8:9], v[8:9], 0, s[52:53]
	v_lshl_add_u64 v[10:11], v[10:11], 0, s[54:55]
	v_lshl_add_u64 v[12:13], v[12:13], 0, s[56:57]
	v_lshl_add_u64 v[14:15], v[14:15], 0, s[58:59]
	s_waitcnt lgkmcnt(0)
	s_barrier
; #define LDSBAR() do { asm volatile("s_waitcnt lgkmcnt(0)" ::: "memory"); __builtin_amdgcn_s_barrier(); asm volatile("" ::: "memory"); } while (0)
; #define HG_STORE(R, s) do { LAS unsigned char* d_ = ring + (s) * HG_SLOT; *(LAS v4u*)(d_ + 16 * tid) = R.q; if (vload) *(LAS v4u*)(d_ + 16384 + 16 * tid) = R.v; *(LAS v4u*)(d_ + 8192 + 16 * tid) = R.l0; \
;         if (tid < 160) *(LAS v4u*)(d_ + 24576 + 16 * tid) = R.l1; } while (0)
; __device__ __forceinline__ void hg_seq(const Frame& F, unsigned char* ws, const float* s0, float* sout, float* Og, int seq, bool sample, int vs_base, int nvs) {
;     ...
;     HgPre R0, R1, R2, R3, R4, R5;
;     R0.l1 = R0.v = (v4u){0u, 0u, 0u, 0u}; R1.l1 = R1.v = (v4u){0u, 0u, 0u, 0u}; R2.l1 = R2.v = (v4u){0u, 0u, 0u, 0u}; R3.l1 = R3.v = (v4u){0u, 0u, 0u, 0u}; R4.l1 = R4.v = (v4u){0u, 0u, 0u, 0u}; R5.l1 = R5.v = (v4u){0u, 0u, 0u, 0u};
;     HG_LOAD(R0, 0); HG_LOAD(R1, 1); HG_LOAD(R2, 2); HG_LOAD(R3, 3); HG_LOAD(R4, 4);
;     HG_STORE(R0, 0); LDSBAR();
;     for (int n = 0; n < nch; n += 6) {
;         HG_LOAD(R5, n + 5); if (active) hg_chunk(ring, S, Ob + (size_t)(n + 0) * 32 * DA, nvalid, vs, lane); if (n + 1 < nch) HG_STORE(R1, 1); LDSBAR(); if (n + 1 >= nch) break;
;         HG_LOAD(R0, n + 6); if (active) hg_chunk(ring + HG_SLOT, S, Ob + (size_t)(n + 1) * 32 * DA, nvalid, vs, lane); if (n + 2 < nch) HG_STORE(R2, 0); LDSBAR(); if (n + 2 >= nch) break;
;         HG_LOAD(R1, n + 7); if (active) hg_chunk(ring, S, Ob + (size_t)(n + 2) * 32 * DA, nvalid, vs, lane); if (n + 3 < nch) HG_STORE(R3, 1); LDSBAR(); if (n + 3 >= nch) break;
;         HG_LOAD(R2, n + 8); if (active) hg_chunk(ring + HG_SLOT, S, Ob + (size_t)(n + 3) * 32 * DA, nvalid, vs, lane); if (n + 4 < nch) HG_STORE(R4, 0); LDSBAR(); if (n + 4 >= nch) break;
;         HG_LOAD(R3, n + 9); if (active) hg_chunk(ring, S, Ob + (size_t)(n + 4) * 32 * DA, nvalid, vs, lane); if (n + 5 < nch) HG_STORE(R5, 1); LDSBAR(); if (n + 5 >= nch) break;
;         HG_LOAD(R4, n + 10); if (active) hg_chunk(ring + HG_SLOT, S, Ob + (size_t)(n + 5) * 32 * DA, nvalid, vs, lane); if (n + 6 < nch) HG_STORE(R0, 0); LDSBAR();
	s_waitcnt vmcnt(28)
	ds_write_b128 v165, v[64:67]
	ds_write_b128 v166, v[68:71]
	ds_write_b128 v167, v[72:75]
	ds_write_b128 v168, v[76:79]
	global_load_dwordx4 v[64:67], v[8:9], off
	global_load_dwordx4 v[68:71], v[10:11], off
	global_load_dwordx4 v[72:75], v[12:13], off
	global_load_dwordx4 v[76:79], v[14:15], off
	v_lshl_add_u64 v[8:9], v[8:9], 0, s[52:53]
	v_lshl_add_u64 v[10:11], v[10:11], 0, s[54:55]
	v_lshl_add_u64 v[12:13], v[12:13], 0, s[56:57]
	v_lshl_add_u64 v[14:15], v[14:15], 0, s[58:59]
	s_waitcnt lgkmcnt(0)
	s_barrier
	s_waitcnt vmcnt(28)
	ds_write_b128 v144, v[80:83]
	ds_write_b128 v145, v[84:87]
	ds_write_b128 v146, v[88:91]
	ds_write_b128 v147, v[92:95]
	global_load_dwordx4 v[80:83], v[8:9], off
	global_load_dwordx4 v[84:87], v[10:11], off
	global_load_dwordx4 v[88:91], v[12:13], off
	global_load_dwordx4 v[92:95], v[14:15], off
	v_lshl_add_u64 v[8:9], v[8:9], 0, s[52:53]
	v_lshl_add_u64 v[10:11], v[10:11], 0, s[54:55]
	v_lshl_add_u64 v[12:13], v[12:13], 0, s[56:57]
	v_lshl_add_u64 v[14:15], v[14:15], 0, s[58:59]
	s_waitcnt lgkmcnt(0)
	s_barrier
	s_waitcnt vmcnt(28)
	ds_write_b128 v148, v[96:99]
	ds_write_b128 v149, v[100:103]
	ds_write_b128 v150, v[104:107]
	ds_write_b128 v151, v[108:111]
	global_load_dwordx4 v[96:99], v[8:9], off
	global_load_dwordx4 v[100:103], v[10:11], off
	global_load_dwordx4 v[104:107], v[12:13], off
	global_load_dwordx4 v[108:111], v[14:15], off
	v_lshl_add_u64 v[8:9], v[8:9], 0, s[52:53]
	v_lshl_add_u64 v[10:11], v[10:11], 0, s[54:55]
	v_lshl_add_u64 v[12:13], v[12:13], 0, s[56:57]
	v_lshl_add_u64 v[14:15], v[14:15], 0, s[58:59]
	s_waitcnt lgkmcnt(0)
	s_barrier
	s_waitcnt vmcnt(28)
	ds_write_b128 v152, v[112:115]
	ds_write_b128 v153, v[116:119]
	ds_write_b128 v154, v[120:123]
	ds_write_b128 v155, v[124:127]
	global_load_dwordx4 v[112:115], v[8:9], off
	global_load_dwordx4 v[116:119], v[10:11], off
	global_load_dwordx4 v[120:123], v[12:13], off
	global_load_dwordx4 v[124:127], v[14:15], off
	v_lshl_add_u64 v[8:9], v[8:9], 0, s[52:53]
	v_lshl_add_u64 v[10:11], v[10:11], 0, s[54:55]
	v_lshl_add_u64 v[12:13], v[12:13], 0, s[56:57]
	v_lshl_add_u64 v[14:15], v[14:15], 0, s[58:59]
	s_waitcnt lgkmcnt(0)
	s_barrier
	s_waitcnt vmcnt(28)
	ds_write_b128 v156, v[128:131]
	ds_write_b128 v157, v[132:135]
	ds_write_b128 v158, v[136:139]
	ds_write_b128 v159, v[140:143]
	global_load_dwordx4 v[128:131], v[8:9], off
	global_load_dwordx4 v[132:135], v[10:11], off
	global_load_dwordx4 v[136:139], v[12:13], off
	global_load_dwordx4 v[140:143], v[14:15], off
	v_lshl_add_u64 v[8:9], v[8:9], 0, s[52:53]
	v_lshl_add_u64 v[10:11], v[10:11], 0, s[54:55]
	v_lshl_add_u64 v[12:13], v[12:13], 0, s[56:57]
	v_lshl_add_u64 v[14:15], v[14:15], 0, s[58:59]
	s_waitcnt lgkmcnt(0)
	s_barrier
	s_waitcnt vmcnt(28)
	ds_write_b128 v160, v[16:19]
	ds_write_b128 v161, v[20:23]
	ds_write_b128 v163, v[24:27]
	ds_write_b128 v164, v[28:31]
	global_load_dwordx4 v[16:19], v[8:9], off
	global_load_dwordx4 v[20:23], v[10:11], off
	global_load_dwordx4 v[24:27], v[12:13], off
	global_load_dwordx4 v[28:31], v[14:15], off
	v_lshl_add_u64 v[8:9], v[8:9], 0, s[52:53]
	v_lshl_add_u64 v[10:11], v[10:11], 0, s[54:55]
	v_lshl_add_u64 v[12:13], v[12:13], 0, s[56:57]
	v_lshl_add_u64 v[14:15], v[14:15], 0, s[58:59]
	s_waitcnt lgkmcnt(0)
	s_barrier
	s_waitcnt vmcnt(28)
	ds_write_b128 v165, v[32:35]
	ds_write_b128 v166, v[36:39]
	ds_write_b128 v167, v[40:43]
	ds_write_b128 v168, v[44:47]
	global_load_dwordx4 v[32:35], v[8:9], off
	global_load_dwordx4 v[36:39], v[10:11], off
	global_load_dwordx4 v[40:43], v[12:13], off
	global_load_dwordx4 v[44:47], v[14:15], off
	v_lshl_add_u64 v[8:9], v[8:9], 0, s[52:53]
	v_lshl_add_u64 v[10:11], v[10:11], 0, s[54:55]
	v_lshl_add_u64 v[12:13], v[12:13], 0, s[56:57]
	v_lshl_add_u64 v[14:15], v[14:15], 0, s[58:59]
	s_waitcnt lgkmcnt(0)
	s_barrier
	s_waitcnt vmcnt(28)
	ds_write_b128 v144, v[48:51]
	ds_write_b128 v145, v[52:55]
	ds_write_b128 v146, v[56:59]
	ds_write_b128 v147, v[60:63]
	global_load_dwordx4 v[48:51], v[8:9], off
	global_load_dwordx4 v[52:55], v[10:11], off
	global_load_dwordx4 v[56:59], v[12:13], off
	global_load_dwordx4 v[60:63], v[14:15], off
	v_lshl_add_u64 v[8:9], v[8:9], 0, s[52:53]
	v_lshl_add_u64 v[10:11], v[10:11], 0, s[54:55]
	v_lshl_add_u64 v[12:13], v[12:13], 0, s[56:57]
	v_lshl_add_u64 v[14:15], v[14:15], 0, s[58:59]
	s_waitcnt lgkmcnt(0)
	s_barrier
	s_waitcnt vmcnt(28)
	ds_write_b128 v148, v[64:67]
	ds_write_b128 v149, v[68:71]
	ds_write_b128 v150, v[72:75]
	ds_write_b128 v151, v[76:79]
	global_load_dwordx4 v[64:67], v[8:9], off
	global_load_dwordx4 v[68:71], v[10:11], off
	global_load_dwordx4 v[72:75], v[12:13], off
	global_load_dwordx4 v[76:79], v[14:15], off
	v_lshl_add_u64 v[8:9], v[8:9], 0, s[52:53]
	v_lshl_add_u64 v[10:11], v[10:11], 0, s[54:55]
	v_lshl_add_u64 v[12:13], v[12:13], 0, s[56:57]
	v_lshl_add_u64 v[14:15], v[14:15], 0, s[58:59]
	s_waitcnt lgkmcnt(0)
	s_barrier
	s_waitcnt vmcnt(28)
	ds_write_b128 v152, v[80:83]
	ds_write_b128 v153, v[84:87]
	ds_write_b128 v154, v[88:91]
	ds_write_b128 v155, v[92:95]
	global_load_dwordx4 v[80:83], v[8:9], off
	global_load_dwordx4 v[84:87], v[10:11], off
	global_load_dwordx4 v[88:91], v[12:13], off
	global_load_dwordx4 v[92:95], v[14:15], off
	v_lshl_add_u64 v[8:9], v[8:9], 0, s[52:53]
	v_lshl_add_u64 v[10:11], v[10:11], 0, s[54:55]
	v_lshl_add_u64 v[12:13], v[12:13], 0, s[56:57]
	v_lshl_add_u64 v[14:15], v[14:15], 0, s[58:59]
	s_waitcnt lgkmcnt(0)
	s_barrier
; #define LDSBAR() do { asm volatile("s_waitcnt lgkmcnt(0)" ::: "memory"); __builtin_amdgcn_s_barrier(); asm volatile("" ::: "memory"); } while (0)
; #define HG_STORE(R, s) do { LAS unsigned char* d_ = ring + (s) * HG_SLOT; *(LAS v4u*)(d_ + 16 * tid) = R.q; if (vload) *(LAS v4u*)(d_ + 16384 + 16 * tid) = R.v; *(LAS v4u*)(d_ + 8192 + 16 * tid) = R.l0; \
;         if (tid < 160) *(LAS v4u*)(d_ + 24576 + 16 * tid) = R.l1; } while (0)
; __device__ __forceinline__ void hg_seq(const Frame& F, unsigned char* ws, const float* s0, float* sout, float* Og, int seq, bool sample, int vs_base, int nvs) {
;     ...
;     HgPre R0, R1, R2, R3, R4, R5;
;     R0.l1 = R0.v = (v4u){0u, 0u, 0u, 0u}; R1.l1 = R1.v = (v4u){0u, 0u, 0u, 0u}; R2.l1 = R2.v = (v4u){0u, 0u, 0u, 0u}; R3.l1 = R3.v = (v4u){0u, 0u, 0u, 0u}; R4.l1 = R4.v = (v4u){0u, 0u, 0u, 0u}; R5.l1 = R5.v = (v4u){0u, 0u, 0u, 0u};
;     HG_LOAD(R0, 0); HG_LOAD(R1, 1); HG_LOAD(R2, 2); HG_LOAD(R3, 3); HG_LOAD(R4, 4);
;     HG_STORE(R0, 0); LDSBAR();
;     for (int n = 0; n < nch; n += 6) {
;         HG_LOAD(R5, n + 5); if (active) hg_chunk(ring, S, Ob + (size_t)(n + 0) * 32 * DA, nvalid, vs, lane); if (n + 1 < nch) HG_STORE(R1, 1); LDSBAR(); if (n + 1 >= nch) break;
;         HG_LOAD(R0, n + 6); if (active) hg_chunk(ring + HG_SLOT, S, Ob + (size_t)(n + 1) * 32 * DA, nvalid, vs, lane); if (n + 2 < nch) HG_STORE(R2, 0); LDSBAR(); if (n + 2 >= nch) break;
;         HG_LOAD(R1, n + 7); if (active) hg_chunk(ring, S, Ob + (size_t)(n + 2) * 32 * DA, nvalid, vs, lane); if (n + 3 < nch) HG_STORE(R3, 1); LDSBAR(); if (n + 3 >= nch) break;
;         HG_LOAD(R2, n + 8); if (active) hg_chunk(ring + HG_SLOT, S, Ob + (size_t)(n + 3) * 32 * DA, nvalid, vs, lane); if (n + 4 < nch) HG_STORE(R4, 0); LDSBAR(); if (n + 4 >= nch) break;
;         HG_LOAD(R3, n + 9); if (active) hg_chunk(ring, S, Ob + (size_t)(n + 4) * 32 * DA, nvalid, vs, lane); if (n + 5 < nch) HG_STORE(R5, 1); LDSBAR(); if (n + 5 >= nch) break;
;         HG_LOAD(R4, n + 10); if (active) hg_chunk(ring + HG_SLOT, S, Ob + (size_t)(n + 5) * 32 * DA, nvalid, vs, lane); if (n + 6 < nch) HG_STORE(R0, 0); LDSBAR();
	s_waitcnt vmcnt(28)
	ds_write_b128 v156, v[96:99]
	ds_write_b128 v157, v[100:103]
	ds_write_b128 v158, v[104:107]
	ds_write_b128 v159, v[108:111]
	global_load_dwordx4 v[96:99], v[8:9], off
	global_load_dwordx4 v[100:103], v[10:11], off
	global_load_dwordx4 v[104:107], v[12:13], off
	global_load_dwordx4 v[108:111], v[14:15], off
	v_lshl_add_u64 v[8:9], v[8:9], 0, s[52:53]
	v_lshl_add_u64 v[10:11], v[10:11], 0, s[54:55]
	v_lshl_add_u64 v[12:13], v[12:13], 0, s[56:57]
	v_lshl_add_u64 v[14:15], v[14:15], 0, s[58:59]
	s_waitcnt lgkmcnt(0)
	s_barrier
	s_waitcnt vmcnt(28)
	ds_write_b128 v160, v[112:115]
	ds_write_b128 v161, v[116:119]
	ds_write_b128 v163, v[120:123]
	ds_write_b128 v164, v[124:127]
	global_load_dwordx4 v[112:115], v[8:9], off
	global_load_dwordx4 v[116:119], v[10:11], off
	global_load_dwordx4 v[120:123], v[12:13], off
	global_load_dwordx4 v[124:127], v[14:15], off
	v_lshl_add_u64 v[8:9], v[8:9], 0, s[52:53]
	v_lshl_add_u64 v[10:11], v[10:11], 0, s[54:55]
	v_lshl_add_u64 v[12:13], v[12:13], 0, s[56:57]
	v_lshl_add_u64 v[14:15], v[14:15], 0, s[58:59]
	s_waitcnt lgkmcnt(0)
	s_barrier
	s_waitcnt vmcnt(28)
	ds_write_b128 v165, v[128:131]
	ds_write_b128 v166, v[132:135]
	ds_write_b128 v167, v[136:139]
	ds_write_b128 v168, v[140:143]
	global_load_dwordx4 v[128:131], v[8:9], off
	global_load_dwordx4 v[132:135], v[10:11], off
	global_load_dwordx4 v[136:139], v[12:13], off
	global_load_dwordx4 v[140:143], v[14:15], off
	v_lshl_add_u64 v[8:9], v[8:9], 0, s[52:53]
	v_lshl_add_u64 v[10:11], v[10:11], 0, s[54:55]
	v_lshl_add_u64 v[12:13], v[12:13], 0, s[56:57]
	v_lshl_add_u64 v[14:15], v[14:15], 0, s[58:59]
	s_waitcnt lgkmcnt(0)
	s_barrier
	s_waitcnt vmcnt(28)
	ds_write_b128 v144, v[16:19]
	ds_write_b128 v145, v[20:23]
	ds_write_b128 v146, v[24:27]
	ds_write_b128 v147, v[28:31]
	global_load_dwordx4 v[16:19], v[8:9], off
	global_load_dwordx4 v[20:23], v[10:11], off
	global_load_dwordx4 v[24:27], v[12:13], off
	global_load_dwordx4 v[28:31], v[14:15], off
	v_lshl_add_u64 v[8:9], v[8:9], 0, s[52:53]
	v_lshl_add_u64 v[10:11], v[10:11], 0, s[54:55]
	v_lshl_add_u64 v[12:13], v[12:13], 0, s[56:57]
	v_lshl_add_u64 v[14:15], v[14:15], 0, s[58:59]
	s_waitcnt lgkmcnt(0)
	s_barrier
	s_waitcnt vmcnt(28)
	ds_write_b128 v148, v[32:35]
	ds_write_b128 v149, v[36:39]
	ds_write_b128 v150, v[40:43]
	ds_write_b128 v151, v[44:47]
	global_load_dwordx4 v[32:35], v[8:9], off
	global_load_dwordx4 v[36:39], v[10:11], off
	global_load_dwordx4 v[40:43], v[12:13], off
	global_load_dwordx4 v[44:47], v[14:15], off
	v_lshl_add_u64 v[8:9], v[8:9], 0, s[52:53]
	v_lshl_add_u64 v[10:11], v[10:11], 0, s[54:55]
	v_lshl_add_u64 v[12:13], v[12:13], 0, s[56:57]
	v_lshl_add_u64 v[14:15], v[14:15], 0, s[58:59]
	s_waitcnt lgkmcnt(0)
	s_barrier
	s_waitcnt vmcnt(28)
	ds_write_b128 v152, v[48:51]
	ds_write_b128 v153, v[52:55]
	ds_write_b128 v154, v[56:59]
	ds_write_b128 v155, v[60:63]
	global_load_dwordx4 v[48:51], v[8:9], off
	global_load_dwordx4 v[52:55], v[10:11], off
	global_load_dwordx4 v[56:59], v[12:13], off
	global_load_dwordx4 v[60:63], v[14:15], off
	v_lshl_add_u64 v[8:9], v[8:9], 0, s[52:53]
	v_lshl_add_u64 v[10:11], v[10:11], 0, s[54:55]
	v_lshl_add_u64 v[12:13], v[12:13], 0, s[56:57]
	v_lshl_add_u64 v[14:15], v[14:15], 0, s[58:59]
	s_waitcnt lgkmcnt(0)
	s_barrier
	s_waitcnt vmcnt(28)
	ds_write_b128 v156, v[64:67]
	ds_write_b128 v157, v[68:71]
	ds_write_b128 v158, v[72:75]
	ds_write_b128 v159, v[76:79]
	global_load_dwordx4 v[64:67], v[8:9], off
	global_load_dwordx4 v[68:71], v[10:11], off
	global_load_dwordx4 v[72:75], v[12:13], off
	global_load_dwordx4 v[76:79], v[14:15], off
	v_lshl_add_u64 v[8:9], v[8:9], 0, s[52:53]
	v_lshl_add_u64 v[10:11], v[10:11], 0, s[54:55]
	v_lshl_add_u64 v[12:13], v[12:13], 0, s[56:57]
	v_lshl_add_u64 v[14:15], v[14:15], 0, s[58:59]
	s_waitcnt lgkmcnt(0)
	s_barrier
; #define LDSBAR() do { asm volatile("s_waitcnt lgkmcnt(0)" ::: "memory"); __builtin_amdgcn_s_barrier(); asm volatile("" ::: "memory"); } while (0)
; #define HG_STORE(R, s) do { LAS unsigned char* d_ = ring + (s) * HG_SLOT; *(LAS v4u*)(d_ + 16 * tid) = R.q; if (vload) *(LAS v4u*)(d_ + 16384 + 16 * tid) = R.v; *(LAS v4u*)(d_ + 8192 + 16 * tid) = R.l0; \
;         if (tid < 160) *(LAS v4u*)(d_ + 24576 + 16 * tid) = R.l1; } while (0)
; __device__ __forceinline__ void hg_seq(const Frame& F, unsigned char* ws, const float* s0, float* sout, float* Og, int seq, bool sample, int vs_base, int nvs) {
;     ...
;     HgPre R0, R1, R2, R3, R4, R5;
;     R0.l1 = R0.v = (v4u){0u, 0u, 0u, 0u}; R1.l1 = R1.v = (v4u){0u, 0u, 0u, 0u}; R2.l1 = R2.v = (v4u){0u, 0u, 0u, 0u}; R3.l1 = R3.v = (v4u){0u, 0u, 0u, 0u}; R4.l1 = R4.v = (v4u){0u, 0u, 0u, 0u}; R5.l1 = R5.v = (v4u){0u, 0u, 0u, 0u};
;     HG_LOAD(R0, 0); HG_LOAD(R1, 1); HG_LOAD(R2, 2); HG_LOAD(R3, 3); HG_LOAD(R4, 4);
;     HG_STORE(R0, 0); LDSBAR();
;     for (int n = 0; n < nch; n += 6) {
;         HG_LOAD(R5, n + 5); if (active) hg_chunk(ring, S, Ob + (size_t)(n + 0) * 32 * DA, nvalid, vs, lane); if (n + 1 < nch) HG_STORE(R1, 1); LDSBAR(); if (n + 1 >= nch) break;
;         HG_LOAD(R0, n + 6); if (active) hg_chunk(ring + HG_SLOT, S, Ob + (size_t)(n + 1) * 32 * DA, nvalid, vs, lane); if (n + 2 < nch) HG_STORE(R2, 0); LDSBAR(); if (n + 2 >= nch) break;
;         HG_LOAD(R1, n + 7); if (active) hg_chunk(ring, S, Ob + (size_t)(n + 2) * 32 * DA, nvalid, vs, lane); if (n + 3 < nch) HG_STORE(R3, 1); LDSBAR(); if (n + 3 >= nch) break;
;         HG_LOAD(R2, n + 8); if (active) hg_chunk(ring + HG_SLOT, S, Ob + (size_t)(n + 3) * 32 * DA, nvalid, vs, lane); if (n + 4 < nch) HG_STORE(R4, 0); LDSBAR(); if (n + 4 >= nch) break;
;         HG_LOAD(R3, n + 9); if (active) hg_chunk(ring, S, Ob + (size_t)(n + 4) * 32 * DA, nvalid, vs, lane); if (n + 5 < nch) HG_STORE(R5, 1); LDSBAR(); if (n + 5 >= nch) break;
;         HG_LOAD(R4, n + 10); if (active) hg_chunk(ring + HG_SLOT, S, Ob + (size_t)(n + 5) * 32 * DA, nvalid, vs, lane); if (n + 6 < nch) HG_STORE(R0, 0); LDSBAR();
	s_waitcnt vmcnt(28)
	ds_write_b128 v160, v[80:83]
	ds_write_b128 v161, v[84:87]
	ds_write_b128 v163, v[88:91]
	ds_write_b128 v164, v[92:95]
	global_load_dwordx4 v[80:83], v[8:9], off
	global_load_dwordx4 v[84:87], v[10:11], off
	global_load_dwordx4 v[88:91], v[12:13], off
	global_load_dwordx4 v[92:95], v[14:15], off
	v_lshl_add_u64 v[8:9], v[8:9], 0, s[52:53]
	v_lshl_add_u64 v[10:11], v[10:11], 0, s[54:55]
	v_lshl_add_u64 v[12:13], v[12:13], 0, s[56:57]
	v_lshl_add_u64 v[14:15], v[14:15], 0, s[58:59]
	s_waitcnt lgkmcnt(0)
	s_barrier
	s_waitcnt vmcnt(28)
	ds_write_b128 v165, v[96:99]
	ds_write_b128 v166, v[100:103]
	ds_write_b128 v167, v[104:107]
	ds_write_b128 v168, v[108:111]
	global_load_dwordx4 v[96:99], v[8:9], off
	global_load_dwordx4 v[100:103], v[10:11], off
	global_load_dwordx4 v[104:107], v[12:13], off
	global_load_dwordx4 v[108:111], v[14:15], off
	v_lshl_add_u64 v[8:9], v[8:9], 0, s[52:53]
	v_lshl_add_u64 v[10:11], v[10:11], 0, s[54:55]
	v_lshl_add_u64 v[12:13], v[12:13], 0, s[56:57]
	v_lshl_add_u64 v[14:15], v[14:15], 0, s[58:59]
	s_waitcnt lgkmcnt(0)
	s_barrier
	s_waitcnt vmcnt(28)
	ds_write_b128 v144, v[112:115]
	ds_write_b128 v145, v[116:119]
	ds_write_b128 v146, v[120:123]
	ds_write_b128 v147, v[124:127]
	global_load_dwordx4 v[112:115], v[8:9], off
	global_load_dwordx4 v[116:119], v[10:11], off
	global_load_dwordx4 v[120:123], v[12:13], off
	global_load_dwordx4 v[124:127], v[14:15], off
	v_lshl_add_u64 v[8:9], v[8:9], 0, s[52:53]
	v_lshl_add_u64 v[10:11], v[10:11], 0, s[54:55]
	v_lshl_add_u64 v[12:13], v[12:13], 0, s[56:57]
	v_lshl_add_u64 v[14:15], v[14:15], 0, s[58:59]
	s_waitcnt lgkmcnt(0)
	s_barrier
	s_waitcnt vmcnt(28)
	ds_write_b128 v148, v[128:131]
	ds_write_b128 v149, v[132:135]
	ds_write_b128 v150, v[136:139]
	ds_write_b128 v151, v[140:143]
	global_load_dwordx4 v[128:131], v[8:9], off
	global_load_dwordx4 v[132:135], v[10:11], off
	global_load_dwordx4 v[136:139], v[12:13], off
	global_load_dwordx4 v[140:143], v[14:15], off
	s_waitcnt lgkmcnt(0)
	s_barrier
	s_waitcnt vmcnt(28)
	ds_write_b128 v152, v[16:19]
	ds_write_b128 v153, v[20:23]
	ds_write_b128 v154, v[24:27]
	ds_write_b128 v155, v[28:31]
	s_waitcnt lgkmcnt(0)
	s_barrier
	s_waitcnt vmcnt(24)
	ds_write_b128 v156, v[32:35]
	ds_write_b128 v157, v[36:39]
	ds_write_b128 v158, v[40:43]
	ds_write_b128 v159, v[44:47]
	s_waitcnt lgkmcnt(0)
	s_barrier
	s_waitcnt vmcnt(20)
	ds_write_b128 v160, v[48:51]
	ds_write_b128 v161, v[52:55]
	ds_write_b128 v163, v[56:59]
	ds_write_b128 v164, v[60:63]
	s_waitcnt lgkmcnt(0)
	s_barrier
	s_waitcnt vmcnt(16)
	ds_write_b128 v165, v[64:67]
	ds_write_b128 v166, v[68:71]
	ds_write_b128 v167, v[72:75]
	ds_write_b128 v168, v[76:79]
	s_waitcnt lgkmcnt(0)
	s_barrier
	s_waitcnt vmcnt(12)
	ds_write_b128 v144, v[80:83]
	ds_write_b128 v145, v[84:87]
	ds_write_b128 v146, v[88:91]
	ds_write_b128 v147, v[92:95]
	s_waitcnt lgkmcnt(0)
	s_barrier
	s_waitcnt vmcnt(8)
	ds_write_b128 v148, v[96:99]
	ds_write_b128 v149, v[100:103]
	ds_write_b128 v150, v[104:107]
	ds_write_b128 v151, v[108:111]
	s_waitcnt lgkmcnt(0)
	s_barrier
	s_waitcnt vmcnt(4)
	ds_write_b128 v152, v[112:115]
	ds_write_b128 v153, v[116:119]
	ds_write_b128 v154, v[120:123]
	ds_write_b128 v155, v[124:127]
	s_waitcnt lgkmcnt(0)
	s_barrier
	s_waitcnt vmcnt(0)
	ds_write_b128 v156, v[128:131]
	ds_write_b128 v157, v[132:135]
	ds_write_b128 v158, v[136:139]
	ds_write_b128 v159, v[140:143]
	s_waitcnt lgkmcnt(0)
	s_barrier
	s_waitcnt lgkmcnt(0)
	s_barrier
	s_waitcnt lgkmcnt(0)
	s_barrier
	s_waitcnt lgkmcnt(0)
	s_barrier
	s_waitcnt lgkmcnt(0)
	s_barrier
	s_waitcnt lgkmcnt(0)
	s_barrier
